# adds batched key loads + nop-free top-k rounds in first-block PEER selection; w_mod GEMV loop unrolled x2 (8 loads in flight)
# speedup vs baseline: 1.0086x; 1.0086x over previous
.LBB0_11:
	s_mov_b32 s100, 0xc000
	s_mov_b32 s101, 0
	s_mul_hi_i32 s0, s18, 0x2aaaaaab
	s_lshr_b32 s1, s0, 31
	s_ashr_i32 s0, s0, 5
	s_add_i32 s6, s0, s1
	s_mul_i32 s0, s6, 0xc0
	s_sub_i32 s0, s18, s0
	s_ashr_i32 s7, s6, 31
	s_lshl_b32 s8, s0, 6
	s_lshl_b64 s[0:1], s[6:7], 11
	v_lshl_add_u64 v[0:1], s[0:1], 0, v[14:15]
	v_mad_u64_u32 v[2:3], s[0:1], v0, s3, v[20:21]
	v_mad_i32_i24 v3, v1, s3, v3
	s_ashr_i32 s9, s8, 31
	v_lshl_add_u64 v[0:1], s[8:9], 2, v[2:3]
	v_lshl_add_u64 v[22:23], v[0:1], 0, v[16:17]
	s_mov_b64 s[14:15], 0
	v_mov_b32_e32 v27, v13
	v_mov_b32_e32 v8, 0
	v_mov_b32_e32 v9, v17
	v_mov_b32_e32 v10, 0
	v_mov_b32_e32 v11, v17
	v_mov_b32_e32 v4, 0
	v_mov_b32_e32 v5, v17
	v_mov_b32_e32 v6, 0
	v_mov_b32_e32 v7, v17
	v_mov_b32_e32 v0, 0
	v_mov_b32_e32 v1, v17
	v_mov_b32_e32 v2, 0
	v_mov_b32_e32 v3, v17
.LBB0_12:
	v_lshl_add_u64 v[100:101], v[22:23], 0, s[14:15]
	v_lshl_add_u64 v[102:103], v[100:101], 0, s[100:101]
	v_lshl_add_u64 v[104:105], v[102:103], 0, s[100:101]
	v_lshl_add_u64 v[106:107], v[104:105], 0, s[100:101]
	v_lshl_add_u64 v[108:109], v[106:107], 0, s[100:101]
	v_lshl_add_u64 v[110:111], v[108:109], 0, s[100:101]
	v_lshl_add_u64 v[112:113], v[110:111], 0, s[100:101]
	v_lshl_add_u64 v[114:115], v[112:113], 0, s[100:101]
	global_load_dwordx4 v[28:31], v[100:101], off
	global_load_dwordx4 v[32:35], v[102:103], off
	global_load_dwordx4 v[36:39], v[104:105], off
	global_load_dwordx4 v[40:43], v[106:107], off
	global_load_dwordx4 v[62:65], v[108:109], off
	global_load_dwordx4 v[66:69], v[110:111], off
	global_load_dwordx4 v[70:73], v[112:113], off
	global_load_dwordx4 v[74:77], v[114:115], off
	s_add_u32 s14, s14, 0x60000
	s_addc_u32 s15, s15, 0
	ds_read_b128 v[44:47], v27
	ds_read_b128 v[48:51], v27 offset:8192
	ds_read_b128 v[52:55], v27 offset:16384
	ds_read_b128 v[78:81], v27 offset:16
	ds_read_b128 v[82:85], v27 offset:8208
	ds_read_b128 v[86:89], v27 offset:16400
	v_add_u32_e32 v27, 32, v27
	s_cmp_lg_u32 s14, 0x300000
	s_waitcnt lgkmcnt(0)
	s_waitcnt vmcnt(7)
	v_pk_fma_f32 v[8:9], v[44:45], v[28:29], v[8:9] op_sel_hi:[0,1,1]
	v_pk_fma_f32 v[10:11], v[44:45], v[30:31], v[10:11] op_sel_hi:[0,1,1]
	v_pk_fma_f32 v[4:5], v[28:29], v[48:49], v[4:5] op_sel_hi:[1,0,1]
	v_pk_fma_f32 v[6:7], v[30:31], v[48:49], v[6:7] op_sel_hi:[1,0,1]
	v_pk_fma_f32 v[0:1], v[28:29], v[52:53], v[0:1] op_sel_hi:[1,0,1]
	v_pk_fma_f32 v[2:3], v[30:31], v[52:53], v[2:3] op_sel_hi:[1,0,1]
	s_waitcnt vmcnt(6)
	v_pk_fma_f32 v[8:9], v[44:45], v[32:33], v[8:9] op_sel:[1,0,0]
	v_pk_fma_f32 v[10:11], v[44:45], v[34:35], v[10:11] op_sel:[1,0,0]
	v_pk_fma_f32 v[4:5], v[32:33], v[48:49], v[4:5] op_sel:[0,1,0]
	v_pk_fma_f32 v[6:7], v[34:35], v[48:49], v[6:7] op_sel:[0,1,0]
	v_pk_fma_f32 v[0:1], v[32:33], v[52:53], v[0:1] op_sel:[0,1,0]
	v_pk_fma_f32 v[2:3], v[34:35], v[52:53], v[2:3] op_sel:[0,1,0]
	s_waitcnt vmcnt(5)
	v_pk_fma_f32 v[8:9], v[46:47], v[36:37], v[8:9] op_sel_hi:[0,1,1]
	v_pk_fma_f32 v[10:11], v[46:47], v[38:39], v[10:11] op_sel_hi:[0,1,1]
	v_pk_fma_f32 v[4:5], v[36:37], v[50:51], v[4:5] op_sel_hi:[1,0,1]
	v_pk_fma_f32 v[6:7], v[38:39], v[50:51], v[6:7] op_sel_hi:[1,0,1]
	v_pk_fma_f32 v[0:1], v[36:37], v[54:55], v[0:1] op_sel_hi:[1,0,1]
	v_pk_fma_f32 v[2:3], v[38:39], v[54:55], v[2:3] op_sel_hi:[1,0,1]
	s_waitcnt vmcnt(4)
	v_pk_fma_f32 v[8:9], v[46:47], v[40:41], v[8:9] op_sel:[1,0,0]
	v_pk_fma_f32 v[10:11], v[46:47], v[42:43], v[10:11] op_sel:[1,0,0]
	v_pk_fma_f32 v[4:5], v[40:41], v[50:51], v[4:5] op_sel:[0,1,0]
	v_pk_fma_f32 v[6:7], v[42:43], v[50:51], v[6:7] op_sel:[0,1,0]
	v_pk_fma_f32 v[0:1], v[40:41], v[54:55], v[0:1] op_sel:[0,1,0]
	v_pk_fma_f32 v[2:3], v[42:43], v[54:55], v[2:3] op_sel:[0,1,0]
	s_waitcnt vmcnt(3)
	v_pk_fma_f32 v[8:9], v[78:79], v[62:63], v[8:9] op_sel_hi:[0,1,1]
	v_pk_fma_f32 v[10:11], v[78:79], v[64:65], v[10:11] op_sel_hi:[0,1,1]
	v_pk_fma_f32 v[4:5], v[62:63], v[82:83], v[4:5] op_sel_hi:[1,0,1]
	v_pk_fma_f32 v[6:7], v[64:65], v[82:83], v[6:7] op_sel_hi:[1,0,1]
	v_pk_fma_f32 v[0:1], v[62:63], v[86:87], v[0:1] op_sel_hi:[1,0,1]
	v_pk_fma_f32 v[2:3], v[64:65], v[86:87], v[2:3] op_sel_hi:[1,0,1]
	s_waitcnt vmcnt(2)
	v_pk_fma_f32 v[8:9], v[78:79], v[66:67], v[8:9] op_sel:[1,0,0]
	v_pk_fma_f32 v[10:11], v[78:79], v[68:69], v[10:11] op_sel:[1,0,0]
	v_pk_fma_f32 v[4:5], v[66:67], v[82:83], v[4:5] op_sel:[0,1,0]
	v_pk_fma_f32 v[6:7], v[68:69], v[82:83], v[6:7] op_sel:[0,1,0]
	v_pk_fma_f32 v[0:1], v[66:67], v[86:87], v[0:1] op_sel:[0,1,0]
	v_pk_fma_f32 v[2:3], v[68:69], v[86:87], v[2:3] op_sel:[0,1,0]
	s_waitcnt vmcnt(1)
	v_pk_fma_f32 v[8:9], v[80:81], v[70:71], v[8:9] op_sel_hi:[0,1,1]
	v_pk_fma_f32 v[10:11], v[80:81], v[72:73], v[10:11] op_sel_hi:[0,1,1]
	v_pk_fma_f32 v[4:5], v[70:71], v[84:85], v[4:5] op_sel_hi:[1,0,1]
	v_pk_fma_f32 v[6:7], v[72:73], v[84:85], v[6:7] op_sel_hi:[1,0,1]
	v_pk_fma_f32 v[0:1], v[70:71], v[88:89], v[0:1] op_sel_hi:[1,0,1]
	v_pk_fma_f32 v[2:3], v[72:73], v[88:89], v[2:3] op_sel_hi:[1,0,1]
	s_waitcnt vmcnt(0)
	v_pk_fma_f32 v[8:9], v[80:81], v[74:75], v[8:9] op_sel:[1,0,0]
	v_pk_fma_f32 v[10:11], v[80:81], v[76:77], v[10:11] op_sel:[1,0,0]
	v_pk_fma_f32 v[4:5], v[74:75], v[84:85], v[4:5] op_sel:[0,1,0]
	v_pk_fma_f32 v[6:7], v[76:77], v[84:85], v[6:7] op_sel:[0,1,0]
	v_pk_fma_f32 v[0:1], v[74:75], v[88:89], v[0:1] op_sel:[0,1,0]
	v_pk_fma_f32 v[2:3], v[76:77], v[88:89], v[2:3] op_sel:[0,1,0]
	s_cbranch_scc1 .LBB0_12
	ds_write_b128 v25, v[8:11] offset:24576
	ds_write_b128 v25, v[4:7] offset:24592
	ds_write_b128 v25, v[0:3] offset:24608
	s_waitcnt lgkmcnt(0)
	s_barrier
	s_and_saveexec_b64 s[0:1], vcc
	s_cbranch_execz .LBB0_10
	v_add_u32_e32 v0, s8, v24
	s_mul_i32 s8, s6, 0xc000
	v_ashrrev_i32_e32 v1, 31, v0
	s_mul_hi_i32 s7, s6, 0xc000
	s_add_u32 s8, s20, s8
	s_addc_u32 s9, s21, s7
	v_lshlrev_b64 v[0:1], 2, v[0:1]
	v_lshl_add_u64 v[2:3], s[8:9], 0, v[0:1]
	global_load_dword v27, v[2:3], off
	ds_read2st64_b32 v[2:3], v26 offset0:96 offset1:99
	ds_read2st64_b32 v[4:5], v26 offset0:102 offset1:105
	ds_read2st64_b32 v[6:7], v26 offset0:108 offset1:111
	ds_read2st64_b32 v[8:9], v26 offset0:114 offset1:117
	ds_read2st64_b32 v[10:11], v26 offset0:120 offset1:123
	ds_read2st64_b32 v[22:23], v26 offset0:126 offset1:129
	ds_read2st64_b32 v[28:29], v26 offset0:132 offset1:135
	ds_read2st64_b32 v[30:31], v26 offset0:138 offset1:141
	ds_read2st64_b32 v[32:33], v26 offset0:144 offset1:147
	ds_read2st64_b32 v[34:35], v26 offset0:150 offset1:153
	ds_read2st64_b32 v[36:37], v26 offset0:156 offset1:159
	ds_read2st64_b32 v[38:39], v26 offset0:162 offset1:165
	ds_read2st64_b32 v[40:41], v26 offset0:168 offset1:171
	ds_read2st64_b32 v[42:43], v26 offset0:174 offset1:177
	ds_read2st64_b32 v[44:45], v26 offset0:180 offset1:183
	ds_read2st64_b32 v[46:47], v26 offset0:186 offset1:189
	s_waitcnt lgkmcnt(14)
	v_add_f32_e32 v2, 0, v2
	v_add_f32_e32 v2, v2, v3
	v_add_f32_e32 v2, v2, v4
	v_add_f32_e32 v2, v2, v5
	s_waitcnt lgkmcnt(13)
	v_add_f32_e32 v2, v2, v6
	v_add_f32_e32 v2, v2, v7
	s_waitcnt lgkmcnt(12)
	v_add_f32_e32 v2, v2, v8
	v_add_f32_e32 v2, v2, v9
	s_waitcnt lgkmcnt(11)
	v_add_f32_e32 v2, v2, v10
	v_add_f32_e32 v2, v2, v11
	s_waitcnt lgkmcnt(10)
	v_add_f32_e32 v2, v2, v22
	v_add_f32_e32 v2, v2, v23
	s_waitcnt lgkmcnt(9)
	v_add_f32_e32 v2, v2, v28
	v_add_f32_e32 v2, v2, v29
	s_waitcnt lgkmcnt(8)
	v_add_f32_e32 v2, v2, v30
	v_add_f32_e32 v2, v2, v31
	s_waitcnt lgkmcnt(7)
	v_add_f32_e32 v2, v2, v32
	v_add_f32_e32 v2, v2, v33
	s_waitcnt lgkmcnt(6)
	v_add_f32_e32 v2, v2, v34
	v_add_f32_e32 v2, v2, v35
	s_waitcnt lgkmcnt(5)
	v_add_f32_e32 v2, v2, v36
	v_add_f32_e32 v2, v2, v37
	s_waitcnt lgkmcnt(4)
	v_add_f32_e32 v2, v2, v38
	v_add_f32_e32 v2, v2, v39
	s_waitcnt lgkmcnt(3)
	v_add_f32_e32 v2, v2, v40
	v_add_f32_e32 v2, v2, v41
	s_waitcnt lgkmcnt(2)
	v_add_f32_e32 v2, v2, v42
	v_add_f32_e32 v2, v2, v43
	s_waitcnt lgkmcnt(1)
	v_add_f32_e32 v2, v2, v44
	v_add_f32_e32 v2, v2, v45
	v_mad_u64_u32 v[48:49], s[6:7], s6, 3, v[18:19]
	v_mov_b64_e32 v[50:51], s[4:5]
	s_waitcnt lgkmcnt(0)
	v_add_f32_e32 v2, v2, v46
	v_mad_i64_i32 v[48:49], s[6:7], v48, s3, v[50:51]
	v_add_f32_e32 v2, v2, v47
	v_lshl_add_u64 v[0:1], v[48:49], 0, v[0:1]
	s_waitcnt vmcnt(0)
	v_add_f32_e32 v2, v2, v27
	global_store_dword v[0:1], v2, off
	s_branch .LBB0_10

.LBB0_454:
	s_mul_i32 s4, s13, 0x2c00
	s_mul_hi_u32 s7, s12, 0x2c00
	s_add_i32 s7, s7, s4
	s_mul_i32 s4, s12, 0x2c00
	s_add_u32 s4, s38, s4
	s_addc_u32 s7, s39, s7
	s_add_u32 s8, s4, 0x1e74b200
	s_addc_u32 s9, s7, 0
	s_lshl_b32 s82, s5, 7
	s_add_u32 s4, s8, s82
	s_addc_u32 s7, s9, 0
	v_add_u32_e32 v146, s10, v170
	s_add_u32 s21, s4, 0x2400
	v_lshlrev_b32_e32 v2, 6, v146
	v_mov_b64_e32 v[0:1], s[8:9]
	s_addc_u32 s23, s7, 0
	v_lshrrev_b32_e32 v157, 6, v169
	v_and_b32_e32 v159, 15, v167
	v_mad_i64_i32 v[0:1], s[10:11], v2, s59, v[0:1]
	s_add_u32 s27, s4, 0x2600
	v_lshl_or_b32 v2, v157, 4, v159
	s_addc_u32 s28, s7, 0
	s_lshl_b32 s4, s5, 8
	v_mul_u32_u24_e32 v2, 0x1600, v2
	v_lshl_add_u64 v[0:1], v[0:1], 0, s[82:83]
	s_add_u32 s4, s8, s4
	v_bfe_u32 v45, v167, 4, 2
	v_lshlrev_b32_e32 v2, 1, v2
	v_mov_b32_e32 v3, v16
	s_addc_u32 s5, s9, 0
	v_lshlrev_b32_e32 v4, 4, v45
	v_mov_b32_e32 v5, v16
	v_lshl_add_u64 v[0:1], v[0:1], 0, v[2:3]
	s_add_u32 s24, s4, 0x2800
	v_lshl_add_u64 v[8:9], v[0:1], 0, v[4:5]
	s_addc_u32 s25, s5, 0
	s_mov_b64 s[0:1], 0x2000
	v_add_co_u32_e32 v10, vcc, s3, v8
	s_mov_b64 s[4:5], 0x2200
	v_lshl_add_u64 v[4:5], v[8:9], 0, s[0:1]
	v_addc_co_u32_e32 v11, vcc, 0, v9, vcc
	v_lshl_add_u64 v[12:13], v[8:9], 0, s[4:5]
	global_load_dwordx4 v[0:3], v[10:11], off
	s_nop 0
	global_load_dwordx4 v[4:7], v[4:5], off offset:64
	s_nop 0
	global_load_dwordx4 v[8:11], v[10:11], off offset:512
	s_nop 0
	global_load_dwordx4 v[18:21], v[12:13], off offset:64
	v_ashrrev_i32_e32 v12, 31, v167
	v_lshrrev_b32_e32 v12, 23, v12
	v_add_u32_e32 v12, v167, v12
	v_ashrrev_i32_e32 v48, 9, v12
	v_mul_i32_i24_e32 v12, 0x200, v48
	v_add_u32_e32 v30, 0x200, v167
	v_sub_u32_e32 v12, v167, v12
	v_ashrrev_i32_e32 v26, 31, v30
	v_ashrrev_i16_e32 v13, 15, v12
	v_lshrrev_b32_e32 v26, 23, v26
	v_lshrrev_b16_e32 v13, 13, v13
	v_add_u32_e32 v26, v30, v26
	v_add_u16_e32 v13, v12, v13
	v_ashrrev_i32_e32 v51, 9, v26
	v_ashrrev_i16_e32 v14, 3, v13
	v_and_b32_e32 v13, -8, v13
	v_mul_i32_i24_e32 v26, 0x200, v51
	v_sub_u16_e32 v12, v12, v13
	v_sub_u32_e32 v26, v30, v26
	v_bfe_i32 v50, v12, 0, 16
	v_add_u32_e32 v12, 0x1ff, v167
	s_movk_i32 s4, 0x3ff
	v_ashrrev_i16_e32 v27, 15, v26
	v_bfe_i32 v49, v14, 0, 16
	v_cmp_gt_u32_e64 s[4:5], s4, v12
	v_mov_b32_e32 v22, s28
	v_mov_b32_e32 v23, s23
	v_mov_b32_e32 v24, s27
	v_mov_b32_e32 v25, s21
	v_lshlrev_b32_e32 v148, 3, v50
	v_lshrrev_b16_e32 v27, 13, v27
	v_cndmask_b32_e64 v35, v22, v23, s[4:5]
	v_cndmask_b32_e64 v34, v24, v25, s[4:5]
	v_mul_hi_i32_i24_e32 v13, 0x2c00, v49
	v_mul_i32_i24_e32 v12, 0x2c00, v49
	v_ashrrev_i32_e32 v149, 31, v148
	v_add_u16_e32 v27, v26, v27
	v_lshl_add_u64 v[12:13], v[34:35], 0, v[12:13]
	v_lshlrev_b64 v[36:37], 1, v[148:149]
	v_ashrrev_i16_e32 v28, 3, v27
	v_and_b32_e32 v27, -8, v27
	v_lshl_add_u64 v[12:13], v[12:13], 0, v[36:37]
	v_sub_u16_e32 v26, v26, v27
	s_add_i32 s29, s6, s26
	global_load_dwordx4 v[12:15], v[12:13], off
	v_bfe_i32 v53, v26, 0, 16
	s_movk_i32 s6, 0xfc00
	v_bfe_i32 v52, v28, 0, 16
	v_cmp_lt_u32_e64 s[6:7], s6, v167
	v_lshlrev_b32_e32 v152, 3, v53
	v_ashrrev_i32_e32 v153, 31, v152
	v_cndmask_b32_e64 v39, v22, v23, s[6:7]
	v_cndmask_b32_e64 v38, v24, v25, s[6:7]
	v_mul_hi_i32_i24_e32 v23, 0x2c00, v52
	v_mul_i32_i24_e32 v22, 0x2c00, v52
	v_lshl_add_u64 v[22:23], v[38:39], 0, v[22:23]
	v_lshlrev_b64 v[40:41], 1, v[152:153]
	v_lshl_add_u64 v[22:23], v[22:23], 0, v[40:41]
	v_lshlrev_b32_e32 v28, 3, v167
	global_load_dwordx4 v[22:25], v[22:23], off
	v_ashrrev_i32_e32 v54, 4, v167
	v_mov_b64_e32 v[42:43], s[24:25]
	v_and_b32_e32 v44, 0x78, v28
	v_mad_i64_i32 v[26:27], s[8:9], v54, s59, v[42:43]
	v_lshlrev_b32_e32 v46, 1, v44
	v_mov_b32_e32 v47, v16
	v_ashrrev_i32_e32 v55, 4, v30
	v_lshl_add_u64 v[26:27], v[26:27], 0, v[46:47]
	v_mad_i64_i32 v[30:31], s[8:9], v55, s59, v[42:43]
	global_load_dwordx4 v[26:29], v[26:27], off
	v_lshl_add_u64 v[30:31], v[30:31], 0, v[46:47]
	global_load_dwordx4 v[30:33], v[30:31], off
	v_lshlrev_b32_e32 v48, 13, v48
	v_lshl_add_u32 v147, v49, 7, v48
	v_lshrrev_b32_e32 v48, 1, v49
	v_bitop3_b32 v48, v48, v50, 7 bitop3:0x6c
	v_lshlrev_b32_e32 v163, 4, v48
	v_add3_u32 v48, 0, v147, v163
	v_mul_lo_u32 v170, v54, s92
	v_mul_lo_u32 v172, v55, s92
	v_lshrrev_b32_e32 v17, 4, v167
	v_lshlrev_b32_e32 v160, 2, v45
	v_add_u32_e32 v181, 0x80, v55
	v_add_u32_e32 v182, 0x80, v54
	v_add_u32_e32 v183, 0x80, v52
	v_add_u32_e32 v214, 0x80, v49
	v_lshlrev_b32_e32 v154, 1, v44
	v_lshlrev_b32_e32 v178, 7, v159
	v_mov_b32_e32 v216, 0
	v_mov_b32_e32 v155, 0xf149f2ca
	v_mov_b32_e32 v217, 0xf149f2ca
	v_mov_b32_e32 v215, 0
	s_waitcnt vmcnt(0)
	ds_write_b128 v48, v[12:15]
	v_lshlrev_b32_e32 v12, 13, v51
	v_lshl_add_u32 v164, v52, 7, v12
	v_lshrrev_b32_e32 v12, 1, v52
	v_bitop3_b32 v12, v12, v53, 7 bitop3:0x6c
	v_lshlrev_b32_e32 v165, 4, v12
	v_add3_u32 v12, 0, v164, v165
	v_lshlrev_b32_e32 v14, 3, v169
	v_and_b32_e32 v15, 64, v191
	v_and_b32_e32 v169, 24, v14
	v_xor_b32_e32 v14, 16, v191
	v_add_u32_e32 v15, 64, v15
	v_cmp_lt_i32_e32 vcc, v14, v15
	ds_write_b128 v12, v[22:25]
	v_lshlrev_b32_e32 v12, 4, v167
	v_and_b32_e32 v171, 0xf0, v12
	v_add3_u32 v12, 0, v170, v171
	v_cndmask_b32_e32 v14, v191, v14, vcc
	v_lshlrev_b32_e32 v161, 2, v14
	v_xor_b32_e32 v14, 32, v191
	v_cmp_lt_i32_e32 vcc, v14, v15
	v_mov_b32_e32 v15, v16
	ds_write_b128 v12, v[26:29] offset:16384
	v_add3_u32 v12, 0, v172, v171
	ds_write_b128 v12, v[30:33] offset:16384
	v_add_u32_e32 v12, 64, v49
	v_mad_u64_u32 v[12:13], s[8:9], v12, s59, v[34:35]
	v_lshl_add_u64 v[12:13], v[12:13], 0, v[36:37]
	s_waitcnt lgkmcnt(0)
	s_barrier
	global_load_dwordx4 v[82:85], v[12:13], off
	v_add_u32_e32 v12, 64, v52
	v_mad_u64_u32 v[12:13], s[8:9], v12, s59, v[38:39]
	v_lshl_add_u64 v[12:13], v[12:13], 0, v[40:41]
	global_load_dwordx4 v[86:89], v[12:13], off
	v_add_u32_e32 v12, 64, v54
	v_mad_i64_i32 v[12:13], s[8:9], v12, s59, v[42:43]
	v_lshl_add_u64 v[12:13], v[12:13], 0, v[46:47]
	global_load_dwordx4 v[90:93], v[12:13], off
	v_add_u32_e32 v12, 64, v55
	v_mad_i64_i32 v[12:13], s[8:9], v12, s59, v[42:43]
	v_lshl_add_u64 v[12:13], v[12:13], 0, v[46:47]
	global_load_dwordx4 v[94:97], v[12:13], off
	v_bfe_u32 v12, v167, 1, 3
	v_cndmask_b32_e32 v14, v191, v14, vcc
	v_bfe_u32 v13, v167, 2, 2
	v_lshlrev_b32_e32 v162, 2, v14
	v_bitop3_b32 v14, v17, v12, 3 bitop3:0x6c
	v_bitop3_b32 v12, v45, v12, 4 bitop3:0x36
	v_mov_b32_e32 v17, v16
	v_lshlrev_b32_e32 v173, 4, v14
	v_lshlrev_b32_e32 v179, 4, v12
	v_or_b32_e32 v12, v160, v13
	v_mov_b32_e32 v14, v16
	v_mov_b64_e32 v[68:69], v[16:17]
	v_mov_b64_e32 v[72:73], v[16:17]
	v_mov_b64_e32 v[56:57], v[16:17]
	v_mov_b64_e32 v[52:53], v[16:17]
	v_mov_b64_e32 v[40:41], v[16:17]
	v_mov_b64_e32 v[36:37], v[16:17]
	v_mov_b64_e32 v[28:29], v[16:17]
	v_mov_b64_e32 v[24:25], v[16:17]
	v_mov_b64_e32 v[80:81], v[16:17]
	v_mov_b64_e32 v[76:77], v[16:17]
	v_mov_b64_e32 v[64:65], v[16:17]
	v_mov_b64_e32 v[60:61], v[16:17]
	v_mov_b64_e32 v[48:49], v[16:17]
	v_mov_b64_e32 v[44:45], v[16:17]
	v_mov_b64_e32 v[32:33], v[16:17]
	v_mul_u32_u24_e32 v180, 0x120, v12
	v_mov_b64_e32 v[66:67], v[14:15]
	v_mov_b64_e32 v[70:71], v[14:15]
	v_mov_b64_e32 v[54:55], v[14:15]
	v_mov_b64_e32 v[50:51], v[14:15]
	v_mov_b64_e32 v[38:39], v[14:15]
	v_mov_b64_e32 v[34:35], v[14:15]
	v_mov_b64_e32 v[26:27], v[14:15]
	v_mov_b64_e32 v[22:23], v[14:15]
	v_mov_b64_e32 v[78:79], v[14:15]
	v_mov_b64_e32 v[74:75], v[14:15]
	v_mov_b64_e32 v[62:63], v[14:15]
	v_mov_b64_e32 v[58:59], v[14:15]
	v_mov_b64_e32 v[46:47], v[14:15]
	v_mov_b64_e32 v[42:43], v[14:15]
	v_mov_b64_e32 v[30:31], v[14:15]
	v_mov_b64_e32 v[12:13], v[14:15]
	v_mov_b64_e32 v[14:15], v[16:17]
	v_add_u32_e32 v197, v178, v179
	v_add_u32_e32 v196, v178, v173
	ds_read_b128 v[220:223], v196
	ds_read_b128 v[224:227], v197
	ds_read_b128 v[228:231], v196 offset:2048
	ds_read_b128 v[232:235], v197 offset:2048
	ds_read_b128 v[236:239], v196 offset:4096
	ds_read_b128 v[240:243], v197 offset:4096
	ds_read_b128 v[244:247], v196 offset:6144
	ds_read_b128 v[248:251], v197 offset:6144

.LBB0_461:
	s_bitcmp1_b32 s31, 0
	s_cselect_b32 s98, 0x8800, 0
	s_add_i32 s30, s30, 2
	s_cmp_ge_u32 s30, s29
	s_waitcnt lgkmcnt(0)
	s_barrier
	v_add_u32_e32 v196, s98, v178
	v_add_u32_e32 v197, v196, v179
	v_add_u32_e32 v196, v196, v173
	ds_read_b128 v[220:223], v196
	ds_read_b128 v[224:227], v197
	ds_read_b128 v[228:231], v196 offset:2048
	ds_read_b128 v[232:235], v197 offset:2048
	ds_read_b128 v[236:239], v196 offset:4096
	ds_read_b128 v[240:243], v197 offset:4096
	ds_read_b128 v[244:247], v196 offset:6144
	ds_read_b128 v[248:251], v197 offset:6144
	s_cbranch_scc1 .LBB0_463
	s_cmp_lt_u32 s30, s26
	s_cselect_b32 s30, 0, s26
	s_cselect_b32 s53, s23, s15
	s_cselect_b32 s61, s28, s17
	s_cselect_b32 s52, s21, s14
	s_cselect_b32 s60, s27, s16
	s_cselect_b32 s49, s25, s19
	s_cselect_b32 s48, s24, s18
	s_cselect_b32 s62, 0x1600, s20
	s_cselect_b32 s63, 0x1600, s22
	v_mov_b32_e32 v17, s61
	s_waitcnt vmcnt(2)
	v_mov_b32_e32 v86, s53
	s_lshl_b32 s30, s30, 6
	v_cndmask_b32_e64 v83, v17, v86, s[4:5]
	v_mov_b32_e32 v88, s60
	v_mov_b32_e32 v89, s52
	v_cndmask_b32_e64 v87, v17, v86, s[6:7]
	v_subrev_u32_e32 v17, s30, v183
	v_cndmask_b32_e64 v82, v88, v89, s[4:5]
	v_cndmask_b32_e64 v86, v88, v89, s[6:7]
	v_mad_i64_i32 v[88:89], s[52:53], s62, v17, 0
	v_subrev_u32_e32 v17, s30, v182
	v_subrev_u32_e32 v84, s30, v214
	s_waitcnt vmcnt(1)
	v_mad_i64_i32 v[90:91], s[52:53], s63, v17, 0
	v_subrev_u32_e32 v17, s30, v181
	v_mad_i64_i32 v[84:85], s[52:53], s62, v84, 0
	v_mad_i64_i32 v[92:93], s[52:53], s63, v17, 0
	v_lshl_add_u64 v[82:83], v[84:85], 1, v[82:83]
	v_lshl_add_u64 v[86:87], v[88:89], 1, v[86:87]
	v_lshl_add_u64 v[90:91], v[90:91], 1, s[48:49]
	v_mov_b32_e32 v155, v16
	v_lshl_add_u64 v[92:93], v[92:93], 1, s[48:49]
	v_lshl_add_u64 v[82:83], v[148:149], 1, v[82:83]
	v_lshl_add_u64 v[86:87], v[152:153], 1, v[86:87]
	v_lshl_add_u64 v[90:91], v[90:91], 0, v[154:155]
	s_waitcnt vmcnt(0)
	v_lshl_add_u64 v[94:95], v[92:93], 0, v[154:155]
	global_load_dwordx4 v[82:85], v[82:83], off
	s_nop 0
	global_load_dwordx4 v[86:89], v[86:87], off
	s_nop 0
	global_load_dwordx4 v[90:93], v[90:91], off
	s_nop 0
	global_load_dwordx4 v[94:97], v[94:95], off

.LBB0_710:
	v_or_b32_e32 v24, s12, v20
	v_mov_b32_e32 v25, v21
	s_lshl_b32 s82, s12, 8
	v_lshlrev_b64 v[24:25], 15, v[24:25]
	v_lshl_add_u64 v[0:1], v[18:19], 0, s[82:83]
	v_lshl_add_u64 v[24:25], v[22:23], 0, v[24:25]
	s_xor_b64 s[8:9], s[10:11], -1
	s_mov_b32 s98, 0x2000
	s_mov_b32 s99, 0
	global_load_dwordx4 v[12:15], v[0:1], off
	global_load_dwordx4 v[8:11], v[0:1], off offset:64
	global_load_dwordx4 v[4:7], v[0:1], off offset:128
	global_load_dwordx4 v[0:3], v[0:1], off offset:192
	v_lshl_add_u64 v[68:69], v[24:25], 0, s[98:99]
	v_lshl_add_u64 v[70:71], v[68:69], 0, s[98:99]
	v_lshl_add_u64 v[72:73], v[70:71], 0, s[98:99]
	v_lshl_add_u64 v[74:75], v[72:73], 0, s[98:99]
	global_load_dwordx4 v[40:43], v[24:25], off
	global_load_dwordx4 v[76:79], v[24:25], off offset:64
	global_load_dwordx4 v[80:83], v[24:25], off offset:128
	global_load_dwordx4 v[84:87], v[24:25], off offset:192
	global_load_dwordx4 v[44:47], v[68:69], off offset:-4096
	global_load_dwordx4 v[88:91], v[68:69], off offset:-4032
	global_load_dwordx4 v[92:95], v[68:69], off offset:-3968
	global_load_dwordx4 v[96:99], v[68:69], off offset:-3904
	global_load_dwordx4 v[48:51], v[68:69], off
	global_load_dwordx4 v[100:103], v[68:69], off offset:64
	global_load_dwordx4 v[104:107], v[68:69], off offset:128
	global_load_dwordx4 v[108:111], v[68:69], off offset:192
	global_load_dwordx4 v[52:55], v[70:71], off offset:-4096
	global_load_dwordx4 v[112:115], v[70:71], off offset:-4032
	global_load_dwordx4 v[116:119], v[70:71], off offset:-3968
	global_load_dwordx4 v[120:123], v[70:71], off offset:-3904
	global_load_dwordx4 v[56:59], v[70:71], off
	global_load_dwordx4 v[124:127], v[70:71], off offset:64
	global_load_dwordx4 v[128:131], v[70:71], off offset:128
	global_load_dwordx4 v[132:135], v[70:71], off offset:192
	global_load_dwordx4 v[60:63], v[72:73], off offset:-4096
	global_load_dwordx4 v[136:139], v[72:73], off offset:-4032
	global_load_dwordx4 v[140:143], v[72:73], off offset:-3968
	global_load_dwordx4 v[144:147], v[72:73], off offset:-3904
	global_load_dwordx4 v[64:67], v[72:73], off
	global_load_dwordx4 v[148:151], v[72:73], off offset:64
	global_load_dwordx4 v[152:155], v[72:73], off offset:128
	global_load_dwordx4 v[156:159], v[72:73], off offset:192
	global_load_dwordx4 v[160:163], v[74:75], off offset:-4096
	global_load_dwordx4 v[164:167], v[74:75], off offset:-4032
	global_load_dwordx4 v[168:171], v[74:75], off offset:-3968
	global_load_dwordx4 v[172:175], v[74:75], off offset:-3904
	s_waitcnt vmcnt(28)
	v_mfma_f32_16x16x32_bf16 v[40:43], v[12:15], v[40:43], 0
	v_mfma_f32_16x16x32_bf16 v[40:43], v[8:11], v[76:79], v[40:43]
	v_mfma_f32_16x16x32_bf16 v[40:43], v[4:7], v[80:83], v[40:43]
	v_mfma_f32_16x16x32_bf16 v[40:43], v[0:3], v[84:87], v[40:43]
	s_waitcnt vmcnt(24)
	v_mfma_f32_16x16x32_bf16 v[44:47], v[12:15], v[44:47], 0
	v_mfma_f32_16x16x32_bf16 v[44:47], v[8:11], v[88:91], v[44:47]
	v_mfma_f32_16x16x32_bf16 v[44:47], v[4:7], v[92:95], v[44:47]
	v_mfma_f32_16x16x32_bf16 v[44:47], v[0:3], v[96:99], v[44:47]
	s_waitcnt vmcnt(20)
	v_mfma_f32_16x16x32_bf16 v[48:51], v[12:15], v[48:51], 0
	v_mfma_f32_16x16x32_bf16 v[48:51], v[8:11], v[100:103], v[48:51]
	v_mfma_f32_16x16x32_bf16 v[48:51], v[4:7], v[104:107], v[48:51]
	v_mfma_f32_16x16x32_bf16 v[48:51], v[0:3], v[108:111], v[48:51]
	s_waitcnt vmcnt(16)
	v_mfma_f32_16x16x32_bf16 v[52:55], v[12:15], v[52:55], 0
	v_mfma_f32_16x16x32_bf16 v[52:55], v[8:11], v[112:115], v[52:55]
	v_mfma_f32_16x16x32_bf16 v[52:55], v[4:7], v[116:119], v[52:55]
	v_mfma_f32_16x16x32_bf16 v[52:55], v[0:3], v[120:123], v[52:55]
	s_waitcnt vmcnt(12)
	v_mfma_f32_16x16x32_bf16 v[56:59], v[12:15], v[56:59], 0
	v_mfma_f32_16x16x32_bf16 v[56:59], v[8:11], v[124:127], v[56:59]
	v_mfma_f32_16x16x32_bf16 v[56:59], v[4:7], v[128:131], v[56:59]
	v_mfma_f32_16x16x32_bf16 v[56:59], v[0:3], v[132:135], v[56:59]
	s_waitcnt vmcnt(8)
	v_mfma_f32_16x16x32_bf16 v[60:63], v[12:15], v[60:63], 0
	v_mfma_f32_16x16x32_bf16 v[60:63], v[8:11], v[136:139], v[60:63]
	v_mfma_f32_16x16x32_bf16 v[60:63], v[4:7], v[140:143], v[60:63]
	v_mfma_f32_16x16x32_bf16 v[60:63], v[0:3], v[144:147], v[60:63]
	s_waitcnt vmcnt(4)
	v_mfma_f32_16x16x32_bf16 v[64:67], v[12:15], v[64:67], 0
	v_mfma_f32_16x16x32_bf16 v[64:67], v[8:11], v[148:151], v[64:67]
	v_mfma_f32_16x16x32_bf16 v[64:67], v[4:7], v[152:155], v[64:67]
	v_mfma_f32_16x16x32_bf16 v[64:67], v[0:3], v[156:159], v[64:67]
	s_waitcnt vmcnt(0)
	v_mfma_f32_16x16x32_bf16 v[12:15], v[12:15], v[160:163], 0
	v_mfma_f32_16x16x32_bf16 v[8:11], v[8:11], v[164:167], v[12:15]
	v_mfma_f32_16x16x32_bf16 v[4:7], v[4:7], v[168:171], v[8:11]
	v_mfma_f32_16x16x32_bf16 v[0:3], v[0:3], v[172:175], v[4:7]
	v_ashrrev_i32_e32 v39, 31, v40
	v_and_b32_e32 v39, 0x7fffff80, v39
	v_and_b32_e32 v40, 0xffffff80, v40
	v_bitop3_b32 v39, v39, v30, v40 bitop3:0xde
	v_ashrrev_i32_e32 v40, 31, v41
	v_and_b32_e32 v40, 0x7fffff80, v40
	v_and_b32_e32 v41, 0xffffff80, v41
	v_bitop3_b32 v40, v40, v30, v41 bitop3:0xde
	v_ashrrev_i32_e32 v41, 31, v42
	v_and_b32_e32 v41, 0x7fffff80, v41
	v_and_b32_e32 v42, 0xffffff80, v42
	v_bitop3_b32 v41, v41, v30, v42 bitop3:0xde
	v_ashrrev_i32_e32 v42, 31, v43
	v_and_b32_e32 v42, 0x7fffff80, v42
	v_and_b32_e32 v43, 0xffffff80, v43
	v_bitop3_b32 v42, v42, v30, v43 bitop3:0xde
	v_ashrrev_i32_e32 v43, 31, v44
	v_and_b32_e32 v43, 0x7fffff80, v43
	v_and_b32_e32 v44, 0xffffff80, v44
	v_bitop3_b32 v43, v43, v31, v44 bitop3:0xde
	v_ashrrev_i32_e32 v44, 31, v45
	v_and_b32_e32 v44, 0x7fffff80, v44
	v_and_b32_e32 v45, 0xffffff80, v45
	v_bitop3_b32 v44, v44, v31, v45 bitop3:0xde
	v_ashrrev_i32_e32 v45, 31, v46
	v_and_b32_e32 v45, 0x7fffff80, v45
	v_and_b32_e32 v46, 0xffffff80, v46
	v_bitop3_b32 v45, v45, v31, v46 bitop3:0xde
	v_ashrrev_i32_e32 v46, 31, v47
	v_and_b32_e32 v46, 0x7fffff80, v46
	v_and_b32_e32 v47, 0xffffff80, v47
	v_bitop3_b32 v46, v46, v31, v47 bitop3:0xde
	v_ashrrev_i32_e32 v47, 31, v48
	v_and_b32_e32 v47, 0x7fffff80, v47
	v_and_b32_e32 v48, 0xffffff80, v48
	v_bitop3_b32 v47, v47, v32, v48 bitop3:0xde
	v_ashrrev_i32_e32 v48, 31, v49
	v_and_b32_e32 v48, 0x7fffff80, v48
	v_and_b32_e32 v49, 0xffffff80, v49
	v_bitop3_b32 v48, v48, v32, v49 bitop3:0xde
	v_ashrrev_i32_e32 v49, 31, v50
	v_and_b32_e32 v49, 0x7fffff80, v49
	v_and_b32_e32 v50, 0xffffff80, v50
	v_bitop3_b32 v49, v49, v32, v50 bitop3:0xde
	v_ashrrev_i32_e32 v50, 31, v51
	v_and_b32_e32 v50, 0x7fffff80, v50
	v_and_b32_e32 v51, 0xffffff80, v51
	v_bitop3_b32 v50, v50, v32, v51 bitop3:0xde
	v_ashrrev_i32_e32 v51, 31, v52
	v_and_b32_e32 v51, 0x7fffff80, v51
	v_and_b32_e32 v52, 0xffffff80, v52
	v_bitop3_b32 v51, v51, v33, v52 bitop3:0xde
	v_ashrrev_i32_e32 v52, 31, v53
	v_and_b32_e32 v52, 0x7fffff80, v52
	v_and_b32_e32 v53, 0xffffff80, v53
	v_bitop3_b32 v52, v52, v33, v53 bitop3:0xde
	v_ashrrev_i32_e32 v53, 31, v54
	v_and_b32_e32 v53, 0x7fffff80, v53
	v_and_b32_e32 v54, 0xffffff80, v54
	v_bitop3_b32 v53, v53, v33, v54 bitop3:0xde
	v_ashrrev_i32_e32 v54, 31, v55
	v_and_b32_e32 v54, 0x7fffff80, v54
	v_and_b32_e32 v55, 0xffffff80, v55
	v_bitop3_b32 v54, v54, v33, v55 bitop3:0xde
	v_ashrrev_i32_e32 v55, 31, v56
	v_and_b32_e32 v55, 0x7fffff80, v55
	v_and_b32_e32 v56, 0xffffff80, v56
	v_bitop3_b32 v55, v55, v34, v56 bitop3:0xde
	v_ashrrev_i32_e32 v56, 31, v57
	v_and_b32_e32 v56, 0x7fffff80, v56
	v_and_b32_e32 v57, 0xffffff80, v57
	v_bitop3_b32 v56, v56, v34, v57 bitop3:0xde
	v_ashrrev_i32_e32 v57, 31, v58
	v_and_b32_e32 v57, 0x7fffff80, v57
	v_and_b32_e32 v58, 0xffffff80, v58
	v_bitop3_b32 v57, v57, v34, v58 bitop3:0xde
	v_ashrrev_i32_e32 v58, 31, v59
	v_and_b32_e32 v58, 0x7fffff80, v58
	v_and_b32_e32 v59, 0xffffff80, v59
	v_bitop3_b32 v58, v58, v34, v59 bitop3:0xde
	v_ashrrev_i32_e32 v59, 31, v60
	v_and_b32_e32 v59, 0x7fffff80, v59
	v_and_b32_e32 v60, 0xffffff80, v60
	v_bitop3_b32 v59, v59, v35, v60 bitop3:0xde
	v_ashrrev_i32_e32 v60, 31, v61
	v_and_b32_e32 v60, 0x7fffff80, v60
	v_and_b32_e32 v61, 0xffffff80, v61
	v_bitop3_b32 v60, v60, v35, v61 bitop3:0xde
	v_ashrrev_i32_e32 v61, 31, v62
	v_and_b32_e32 v61, 0x7fffff80, v61
	v_and_b32_e32 v62, 0xffffff80, v62
	v_bitop3_b32 v61, v61, v35, v62 bitop3:0xde
	v_ashrrev_i32_e32 v62, 31, v63
	v_and_b32_e32 v62, 0x7fffff80, v62
	v_and_b32_e32 v63, 0xffffff80, v63
	v_bitop3_b32 v62, v62, v35, v63 bitop3:0xde
	v_ashrrev_i32_e32 v63, 31, v64
	v_and_b32_e32 v63, 0x7fffff80, v63
	v_and_b32_e32 v64, 0xffffff80, v64
	v_bitop3_b32 v63, v63, v36, v64 bitop3:0xde
	v_ashrrev_i32_e32 v64, 31, v65
	v_and_b32_e32 v64, 0x7fffff80, v64
	v_and_b32_e32 v65, 0xffffff80, v65
	v_bitop3_b32 v64, v64, v36, v65 bitop3:0xde
	v_ashrrev_i32_e32 v65, 31, v66
	v_and_b32_e32 v65, 0x7fffff80, v65
	v_and_b32_e32 v66, 0xffffff80, v66
	v_bitop3_b32 v65, v65, v36, v66 bitop3:0xde
	v_ashrrev_i32_e32 v66, 31, v67
	v_and_b32_e32 v66, 0x7fffff80, v66
	v_and_b32_e32 v67, 0xffffff80, v67
	v_bitop3_b32 v66, v66, v36, v67 bitop3:0xde
	v_ashrrev_i32_e32 v4, 31, v0
	v_and_b32_e32 v4, 0x7fffff80, v4
	v_and_b32_e32 v0, 0xffffff80, v0
	v_bitop3_b32 v0, v4, v37, v0 bitop3:0xde
	v_ashrrev_i32_e32 v4, 31, v1
	v_and_b32_e32 v4, 0x7fffff80, v4
	v_and_b32_e32 v1, 0xffffff80, v1
	v_bitop3_b32 v1, v4, v37, v1 bitop3:0xde
	v_ashrrev_i32_e32 v4, 31, v2
	v_and_b32_e32 v4, 0x7fffff80, v4
	v_and_b32_e32 v2, 0xffffff80, v2
	v_bitop3_b32 v2, v4, v37, v2 bitop3:0xde
	v_ashrrev_i32_e32 v4, 31, v3
	v_and_b32_e32 v4, 0x7fffff80, v4
	v_and_b32_e32 v3, 0xffffff80, v3
	v_bitop3_b32 v3, v4, v37, v3 bitop3:0xde
	v_lshl_add_u32 v4, s12, 6, v38
	s_mov_b32 s12, 0
	s_branch .LBB0_712
.LBB0_711:
	s_or_b64 exec, exec, s[10:11]
	s_add_i32 s12, s12, 4
	v_cmp_ne_u32_e32 vcc, v42, v9
	v_cmp_ne_u32_e64 s[98:99], v46, v9
	v_cmp_ne_u32_e64 s[100:101], v50, v9
	v_cndmask_b32_e32 v42, v195, v42, vcc
	v_cndmask_b32_e64 v46, v195, v46, s[98:99]
	v_cndmask_b32_e64 v50, v195, v50, s[100:101]
	v_cmp_ne_u32_e32 vcc, v54, v9
	v_cmp_ne_u32_e64 s[98:99], v58, v9
	v_cmp_ne_u32_e64 s[100:101], v62, v9
	v_cndmask_b32_e32 v54, v195, v54, vcc
	v_cndmask_b32_e64 v58, v195, v58, s[98:99]
	v_cndmask_b32_e64 v62, v195, v62, s[100:101]
	v_cmp_ne_u32_e32 vcc, v66, v9
	v_cmp_ne_u32_e64 s[98:99], v3, v9
	v_cmp_ne_u32_e64 s[100:101], v41, v8
	v_cndmask_b32_e32 v66, v195, v66, vcc
	v_cndmask_b32_e64 v3, v195, v3, s[98:99]
	v_cndmask_b32_e64 v41, v195, v41, s[100:101]
	v_cmp_ne_u32_e32 vcc, v45, v8
	v_cmp_ne_u32_e64 s[98:99], v49, v8
	v_cmp_ne_u32_e64 s[100:101], v53, v8
	v_cndmask_b32_e32 v45, v195, v45, vcc
	v_cndmask_b32_e64 v49, v195, v49, s[98:99]
	v_cndmask_b32_e64 v53, v195, v53, s[100:101]
	v_cmp_ne_u32_e32 vcc, v57, v8
	v_cmp_ne_u32_e64 s[98:99], v61, v8
	v_cmp_ne_u32_e64 s[100:101], v65, v8
	v_cndmask_b32_e32 v57, v195, v57, vcc
	v_cndmask_b32_e64 v61, v195, v61, s[98:99]
	v_cndmask_b32_e64 v65, v195, v65, s[100:101]
	v_cmp_ne_u32_e32 vcc, v2, v8
	v_cmp_ne_u32_e64 s[98:99], v40, v6
	v_cmp_ne_u32_e64 s[100:101], v44, v6
	v_cndmask_b32_e32 v2, v195, v2, vcc
	v_cndmask_b32_e64 v40, v195, v40, s[98:99]
	v_cndmask_b32_e64 v44, v195, v44, s[100:101]
	v_cmp_ne_u32_e32 vcc, v48, v6
	v_cmp_ne_u32_e64 s[98:99], v52, v6
	v_cmp_ne_u32_e64 s[100:101], v56, v6
	v_cndmask_b32_e32 v48, v195, v48, vcc
	v_cndmask_b32_e64 v52, v195, v52, s[98:99]
	v_cndmask_b32_e64 v56, v195, v56, s[100:101]
	v_cmp_ne_u32_e32 vcc, v60, v6
	v_cmp_ne_u32_e64 s[98:99], v64, v6
	v_cmp_ne_u32_e64 s[100:101], v1, v6
	v_cndmask_b32_e32 v60, v195, v60, vcc
	v_cndmask_b32_e64 v64, v195, v64, s[98:99]
	v_cndmask_b32_e64 v1, v195, v1, s[100:101]
	v_cmp_ne_u32_e32 vcc, v39, v5
	v_cmp_ne_u32_e64 s[98:99], v43, v5
	v_cmp_ne_u32_e64 s[100:101], v47, v5
	v_cndmask_b32_e32 v39, v195, v39, vcc
	v_cndmask_b32_e64 v43, v195, v43, s[98:99]
	v_cndmask_b32_e64 v47, v195, v47, s[100:101]
	v_cmp_ne_u32_e32 vcc, v51, v5
	v_cmp_ne_u32_e64 s[98:99], v55, v5
	v_cmp_ne_u32_e64 s[100:101], v59, v5
	v_cndmask_b32_e32 v51, v195, v51, vcc
	v_cndmask_b32_e64 v55, v195, v55, s[98:99]
	v_cndmask_b32_e64 v59, v195, v59, s[100:101]
	v_cmp_ne_u32_e32 vcc, v63, v5
	v_cmp_ne_u32_e64 s[98:99], v0, v5
	s_nop 0
	v_cndmask_b32_e32 v63, v195, v63, vcc
	v_cndmask_b32_e64 v0, v195, v0, s[98:99]
	s_cmp_lg_u32 s12, 64
	s_cbranch_scc0 .LBB0_709
.LBB0_712:
	v_max3_i32 v5, v39, v43, v47
	v_max3_i32 v6, v40, v44, v48
	v_max3_i32 v8, v41, v45, v49
	v_max3_i32 v9, v42, v46, v50
	v_max3_i32 v5, v5, v51, v55
	v_max3_i32 v6, v6, v52, v56
	v_max3_i32 v8, v8, v53, v57
	v_max3_i32 v9, v9, v54, v58
	v_max3_i32 v5, v5, v59, v63
	v_max3_i32 v6, v6, v60, v64
	v_max3_i32 v8, v8, v61, v65
	v_max3_i32 v9, v9, v62, v66
	v_max_i32_e32 v5, v5, v0
	v_max_i32_e32 v6, v6, v1
	v_max_i32_e32 v8, v8, v2
	v_max_i32_e32 v9, v9, v3
	v_max_i32_dpp v5, v5, v5 quad_perm:[1,0,3,2] row_mask:0xf bank_mask:0xf bound_ctrl:1
	v_max_i32_dpp v6, v6, v6 quad_perm:[1,0,3,2] row_mask:0xf bank_mask:0xf bound_ctrl:1
	v_max_i32_dpp v8, v8, v8 quad_perm:[1,0,3,2] row_mask:0xf bank_mask:0xf bound_ctrl:1
	v_max_i32_dpp v9, v9, v9 quad_perm:[1,0,3,2] row_mask:0xf bank_mask:0xf bound_ctrl:1
	v_max_i32_dpp v5, v5, v5 quad_perm:[2,3,0,1] row_mask:0xf bank_mask:0xf bound_ctrl:1
	v_max_i32_dpp v6, v6, v6 quad_perm:[2,3,0,1] row_mask:0xf bank_mask:0xf bound_ctrl:1
	v_max_i32_dpp v8, v8, v8 quad_perm:[2,3,0,1] row_mask:0xf bank_mask:0xf bound_ctrl:1
	v_max_i32_dpp v9, v9, v9 quad_perm:[2,3,0,1] row_mask:0xf bank_mask:0xf bound_ctrl:1
	v_max_i32_dpp v5, v5, v5 row_half_mirror row_mask:0xf bank_mask:0xf bound_ctrl:1
	v_max_i32_dpp v6, v6, v6 row_half_mirror row_mask:0xf bank_mask:0xf bound_ctrl:1
	v_max_i32_dpp v8, v8, v8 row_half_mirror row_mask:0xf bank_mask:0xf bound_ctrl:1
	v_max_i32_dpp v9, v9, v9 row_half_mirror row_mask:0xf bank_mask:0xf bound_ctrl:1
	v_max_i32_dpp v5, v5, v5 row_mirror row_mask:0xf bank_mask:0xf bound_ctrl:1
	v_max_i32_dpp v6, v6, v6 row_mirror row_mask:0xf bank_mask:0xf bound_ctrl:1
	v_max_i32_dpp v8, v8, v8 row_mirror row_mask:0xf bank_mask:0xf bound_ctrl:1
	v_max_i32_dpp v9, v9, v9 row_mirror row_mask:0xf bank_mask:0xf bound_ctrl:1
	v_add_u32_e32 v7, s12, v4
	s_and_saveexec_b64 s[10:11], s[6:7]
	s_cbranch_execz .LBB0_711
	v_and_b32_e32 v67, 0xffffff80, v5
	v_ashrrev_i32_e32 v68, 31, v5
	v_bitop3_b32 v67, v68, v67, s81 bitop3:0x6c
	v_bitop3_b32 v68, v5, s58, v5 bitop3:0xc
	ds_write2st64_b32 v7, v67, v68 offset1:32
	v_and_b32_e32 v69, 0xffffff80, v6
	v_ashrrev_i32_e32 v70, 31, v6
	v_bitop3_b32 v69, v70, v69, s81 bitop3:0x6c
	v_bitop3_b32 v70, v6, s58, v6 bitop3:0xc
	ds_write2st64_b32 v7, v69, v70 offset0:2 offset1:34
	v_and_b32_e32 v71, 0xffffff80, v8
	v_ashrrev_i32_e32 v72, 31, v8
	v_bitop3_b32 v71, v72, v71, s81 bitop3:0x6c
	v_bitop3_b32 v72, v8, s58, v8 bitop3:0xc
	ds_write2st64_b32 v7, v71, v72 offset0:4 offset1:36
	v_and_b32_e32 v73, 0xffffff80, v9
	v_ashrrev_i32_e32 v74, 31, v9
	v_bitop3_b32 v73, v74, v73, s81 bitop3:0x6c
	v_bitop3_b32 v74, v9, s58, v9 bitop3:0xc
	ds_write2st64_b32 v7, v73, v74 offset0:6 offset1:38
	s_branch .LBB0_711

	.amdhsa_kernel _Z11mega_kernel6Params6Inputs
		.amdhsa_group_segment_fixed_size 0
		.amdhsa_private_segment_fixed_size 0
		.amdhsa_kernarg_size 480
		.amdhsa_user_sgpr_count 2
		.amdhsa_user_sgpr_dispatch_ptr 0
		.amdhsa_user_sgpr_queue_ptr 0
		.amdhsa_user_sgpr_kernarg_segment_ptr 1
		.amdhsa_user_sgpr_dispatch_id 0
		.amdhsa_user_sgpr_kernarg_preload_length 0
		.amdhsa_user_sgpr_kernarg_preload_offset 0
		.amdhsa_user_sgpr_private_segment_size 0
		.amdhsa_uses_dynamic_stack 0
		.amdhsa_enable_private_segment 0
		.amdhsa_system_sgpr_workgroup_id_x 1
		.amdhsa_system_sgpr_workgroup_id_y 0
		.amdhsa_system_sgpr_workgroup_id_z 0
		.amdhsa_system_sgpr_workgroup_info 0
		.amdhsa_system_vgpr_workitem_id 0
		.amdhsa_next_free_vgpr 256
		.amdhsa_next_free_sgpr 102
		.amdhsa_accum_offset 256
		.amdhsa_reserve_vcc 1
		.amdhsa_float_round_mode_32 0
		.amdhsa_float_round_mode_16_64 0
		.amdhsa_float_denorm_mode_32 3
		.amdhsa_float_denorm_mode_16_64 3
		.amdhsa_dx10_clamp 1
		.amdhsa_ieee_mode 1
		.amdhsa_fp16_overflow 0
		.amdhsa_tg_split 0
		.amdhsa_exception_fp_ieee_invalid_op 0
		.amdhsa_exception_fp_denorm_src 0
		.amdhsa_exception_fp_ieee_div_zero 0
		.amdhsa_exception_fp_ieee_overflow 0
		.amdhsa_exception_fp_ieee_underflow 0
		.amdhsa_exception_fp_ieee_inexact 0
		.amdhsa_exception_int_div_zero 0
	.end_amdhsa_kernel

amdhsa.kernels:
  - .agpr_count:     0
    .args:
      - .offset:         0
        .size:           16
        .value_kind:     by_value
      - .offset:         16
        .size:           208
        .value_kind:     by_value
      - .offset:         224
        .size:           4
        .value_kind:     hidden_block_count_x
      - .offset:         228
        .size:           4
        .value_kind:     hidden_block_count_y
      - .offset:         232
        .size:           4
        .value_kind:     hidden_block_count_z
      - .offset:         236
        .size:           2
        .value_kind:     hidden_group_size_x
      - .offset:         238
        .size:           2
        .value_kind:     hidden_group_size_y
      - .offset:         240
        .size:           2
        .value_kind:     hidden_group_size_z
      - .offset:         242
        .size:           2
        .value_kind:     hidden_remainder_x
      - .offset:         244
        .size:           2
        .value_kind:     hidden_remainder_y
      - .offset:         246
        .size:           2
        .value_kind:     hidden_remainder_z
      - .offset:         264
        .size:           8
        .value_kind:     hidden_global_offset_x
      - .offset:         272
        .size:           8
        .value_kind:     hidden_global_offset_y
      - .offset:         280
        .size:           8
        .value_kind:     hidden_global_offset_z
      - .offset:         288
        .size:           2
        .value_kind:     hidden_grid_dims
      - .offset:         344
        .size:           4
        .value_kind:     hidden_dynamic_lds_size
    .group_segment_fixed_size: 0
    .kernarg_segment_align: 8
    .kernarg_segment_size: 480
    .language:       OpenCL C
    .language_version:
      - 2
      - 0
    .max_flat_workgroup_size: 512
    .name:           _Z11mega_kernel6Params6Inputs
    .private_segment_fixed_size: 0
    .sgpr_count:     108
    .sgpr_spill_count: 109
    .symbol:         _Z11mega_kernel6Params6Inputs.kd
    .uniform_work_group_size: 1
    .uses_dynamic_stack: false
    .vgpr_count:     256
    .vgpr_spill_count: 0
    .wavefront_size: 64
